# 7.11 loop-edge rotation also in the NA tile loop: next tile's address math + 4 global loads in front of the per-tile barrier
# baseline (speedup 1.0000x reference)
.LBB0_337:
	s_or_b64 exec, exec, s[38:39]
	v_bitop3_b32 v66, s15, v141, 64 bitop3:0xde
	v_mul_u32_u24_e32 v66, 0x48, v66
	v_lshl_add_u32 v66, v66, 1, v146
	s_waitcnt vmcnt(3)
	ds_write_b128 v66, v[50:53]
	s_waitcnt vmcnt(2)
	ds_write_b128 v66, v[54:57] offset:18432
	v_bitop3_b32 v50, s15, v143, 64 bitop3:0xde
	s_add_i32 s24, s24, 1
	v_mul_u32_u24_e32 v50, 0x48, v50
	s_add_i32 s14, s14, 64
	v_lshl_add_u32 v50, v50, 1, v146
	s_cmp_lg_u32 s24, 12
	v_add_u32_e32 v147, 0x7c, v147
	s_waitcnt vmcnt(1)
	ds_write_b128 v50, v[58:61]
	s_waitcnt vmcnt(0)
	ds_write_b128 v50, v[62:65] offset:18432
	s_waitcnt lgkmcnt(0)
	s_cbranch_scc0 .Lna_rot_skip
	s_cmp_gt_u32 s24, 7
	s_mov_b64 s[2:3], -1
	s_cbranch_scc0 .Lnarot_BB0_340
	v_add_u32_e32 v58, s14, v149
	s_mov_b64 s[2:3], 0

.Lna_rot_skip:
	s_cmp_lg_u32 s24, 12
	s_barrier
	s_cbranch_scc0 .LBB0_419
	s_branch .Lna_rot_body

.Lna_rot_body:
	s_and_b32 s15, s14, 64
	v_add_u32_e32 v66, s24, v148
	s_cmp_gt_u32 s24, 8
	s_cselect_b64 s[10:11], -1, 0
	s_cmp_lt_u32 s24, 9
	v_cmp_gt_u32_e32 vcc, 8, v66
	s_movk_i32 s13, 0x1800
	s_cselect_b64 s[28:29], -1, 0
	s_or_b64 s[2:3], s[10:11], vcc
	s_and_saveexec_b64 s[38:39], s[2:3]
	s_cbranch_execz .LBB0_337
	v_or_b32_e32 v66, s15, v138
	v_mad_u32_u24 v82, v66, s16, v145
	s_cmp_lt_u32 s24, 9
	s_cbranch_scc0 .Lna_ctx_tile
	s_bitcmp1_b32 s100, 6
	s_cbranch_scc1 .Lna_loc_h1
	ds_read_b128 v[164:167], v82 offset:0
	ds_read_b128 v[168:171], v82 offset:64
	ds_read_b128 v[172:175], v82 offset:2304
	ds_read_b128 v[176:179], v82 offset:2368
	ds_read_b128 v[180:183], v82 offset:4608
	ds_read_b128 v[184:187], v82 offset:4672
	ds_read2_b32 v[224:225], v147 offset0:16 offset1:17
	ds_read2_b32 v[226:227], v147 offset0:18 offset1:19
	ds_read2_b32 v[228:229], v147 offset0:32 offset1:33
	ds_read2_b32 v[230:231], v147 offset0:34 offset1:35
	v_mov_b32_e32 v158, 0xf149f2ca
	s_waitcnt lgkmcnt(9)
	v_mfma_f32_16x16x32_bf16 v[90:93], v[164:167], v[38:41], 0
	s_waitcnt lgkmcnt(8)
	v_mfma_f32_16x16x32_bf16 v[90:93], v[168:171], v[34:37], v[90:93]
	s_waitcnt lgkmcnt(7)
	v_mfma_f32_16x16x32_bf16 v[94:97], v[172:175], v[38:41], 0
	s_waitcnt lgkmcnt(6)
	v_mfma_f32_16x16x32_bf16 v[94:97], v[176:179], v[34:37], v[94:97]
	ds_read2_b32 v[232:233], v147 offset0:0 offset1:1
	ds_read2_b32 v[234:235], v147 offset0:2 offset1:3
	ds_read2_b32 v[236:237], v147 offset0:16 offset1:17
	ds_read2_b32 v[238:239], v147 offset0:18 offset1:19
	ds_read2_b32 v[240:241], v147 offset0:32 offset1:33
	ds_read2_b32 v[242:243], v147 offset0:34 offset1:35
	v_mfma_f32_16x16x32_bf16 v[98:101], v[164:167], v[46:49], 0
	v_or_b32_e32 v160, s15, v135
	v_mul_u32_u24_e32 v160, 0x48, v160
	v_lshl_add_u32 v160, v160, 1, v136
	s_waitcnt lgkmcnt(6)
	v_fmac_f32_e32 v224, 0x3e38aa3b, v90
	v_mfma_f32_16x16x32_bf16 v[98:101], v[168:171], v[42:45], v[98:101]
	v_fmac_f32_e32 v225, 0x3e38aa3b, v91
	v_fmac_f32_e32 v226, 0x3e38aa3b, v92
	v_fmac_f32_e32 v227, 0x3e38aa3b, v93
	v_fmac_f32_e32 v228, 0x3e38aa3b, v94
	v_mfma_f32_16x16x32_bf16 v[102:105], v[172:175], v[46:49], 0
	v_fmac_f32_e32 v229, 0x3e38aa3b, v95
	v_fmac_f32_e32 v230, 0x3e38aa3b, v96
	v_fmac_f32_e32 v231, 0x3e38aa3b, v97
	v_cndmask_b32_e64 v224, v158, v224, s[40:41]
	v_mfma_f32_16x16x32_bf16 v[102:105], v[176:179], v[42:45], v[102:105]
	v_cndmask_b32_e64 v225, v158, v225, s[42:43]
	v_cndmask_b32_e64 v226, v158, v226, s[44:45]
	v_cndmask_b32_e64 v227, v158, v227, s[46:47]
	v_cndmask_b32_e64 v228, v158, v228, s[48:49]
	v_mfma_f32_16x16x32_bf16 v[106:109], v[180:183], v[46:49], 0
	v_cndmask_b32_e64 v229, v158, v229, s[50:51]
	v_cndmask_b32_e64 v230, v158, v230, s[52:53]
	v_cndmask_b32_e64 v231, v158, v231, s[54:55]
	v_max3_f32 v150, v224, s18, v225
	v_mfma_f32_16x16x32_bf16 v[106:109], v[184:187], v[42:45], v[106:109]
	v_max3_f32 v150, v150, v226, v227
	v_max3_f32 v150, v150, v228, v229
	v_max3_f32 v150, v150, v230, v231
	s_waitcnt lgkmcnt(0)
	ds_read_b64_tr_b16 v[164:165], v160 offset:18432
	ds_read_b64_tr_b16 v[166:167], v160 offset:20736
	ds_read_b64_tr_b16 v[168:169], v160 offset:18464
	ds_read_b64_tr_b16 v[170:171], v160 offset:20768
	ds_read_b64_tr_b16 v[172:173], v160 offset:23040
	ds_read_b64_tr_b16 v[174:175], v160 offset:25344
	ds_read_b64_tr_b16 v[176:177], v160 offset:23072
	ds_read_b64_tr_b16 v[178:179], v160 offset:25376
	v_fmac_f32_e32 v232, 0x3e38aa3b, v98
	v_fmac_f32_e32 v233, 0x3e38aa3b, v99
	v_fmac_f32_e32 v234, 0x3e38aa3b, v100
	v_fmac_f32_e32 v235, 0x3e38aa3b, v101
	v_fmac_f32_e32 v236, 0x3e38aa3b, v102
	v_fmac_f32_e32 v237, 0x3e38aa3b, v103
	v_fmac_f32_e32 v238, 0x3e38aa3b, v104
	v_fmac_f32_e32 v239, 0x3e38aa3b, v105
	v_fmac_f32_e32 v240, 0x3e38aa3b, v106
	v_fmac_f32_e32 v241, 0x3e38aa3b, v107
	v_fmac_f32_e32 v242, 0x3e38aa3b, v108
	v_fmac_f32_e32 v243, 0x3e38aa3b, v109
	v_cndmask_b32_e64 v232, v158, v232, s[72:73]
	v_cndmask_b32_e64 v233, v158, v233, s[74:75]
	v_cndmask_b32_e64 v234, v158, v234, s[76:77]
	v_cndmask_b32_e64 v235, v158, v235, s[78:79]
	v_cndmask_b32_e64 v236, v158, v236, s[80:81]
	v_cndmask_b32_e64 v237, v158, v237, s[82:83]
	v_cndmask_b32_e64 v238, v158, v238, s[84:85]
	v_cndmask_b32_e64 v239, v158, v239, s[86:87]
	v_cndmask_b32_e64 v240, v158, v240, s[88:89]
	v_cndmask_b32_e64 v241, v158, v241, s[90:91]
	v_cndmask_b32_e64 v242, v158, v242, s[92:93]
	v_cndmask_b32_e64 v243, v158, v243, s[4:5]
	v_max3_f32 v151, v232, s18, v233
	v_max3_f32 v151, v151, v234, v235
	v_max3_f32 v151, v151, v236, v237
	v_max3_f32 v151, v151, v238, v239
	v_max3_f32 v151, v151, v240, v241
	v_max3_f32 v151, v151, v242, v243
	v_mov_b32_e32 v152, v150
	v_mov_b32_e32 v153, v151
	s_nop 0
	v_permlane16_swap_b32_e32 v152, v150
	v_permlane16_swap_b32_e32 v153, v151
	v_max_f32_e32 v150, v150, v152
	v_max_f32_e32 v151, v151, v153
	v_mov_b32_e32 v152, v150
	v_mov_b32_e32 v153, v151
	s_nop 0
	v_permlane32_swap_b32_e32 v152, v150
	v_permlane32_swap_b32_e32 v153, v151
	v_max_f32_e32 v150, v150, v152
	v_max_f32_e32 v151, v151, v153
	v_add_f32_e32 v110, 0x41000000, v144
	v_cmp_gt_f32_e32 vcc, v150, v110
	s_cbranch_vccz .Lna_l0_keep0
	v_max_f32_e32 v244, v144, v150
	v_sub_f32_e32 v110, v144, v244
	v_exp_f32_e32 v110, v110
	v_mov_b32_e32 v144, v244
	v_mul_f32_e32 v140, v140, v110
	v_pk_mul_f32 v[18:19], v[18:19], v[110:111] op_sel_hi:[1,0]
	v_pk_mul_f32 v[20:21], v[20:21], v[110:111] op_sel_hi:[1,0]
	v_pk_mul_f32 v[22:23], v[22:23], v[110:111] op_sel_hi:[1,0]
	v_pk_mul_f32 v[24:25], v[24:25], v[110:111] op_sel_hi:[1,0]
	v_pk_mul_f32 v[10:11], v[10:11], v[110:111] op_sel_hi:[1,0]
	v_pk_mul_f32 v[12:13], v[12:13], v[110:111] op_sel_hi:[1,0]
	v_pk_mul_f32 v[2:3], v[2:3], v[110:111] op_sel_hi:[1,0]
	v_pk_mul_f32 v[4:5], v[4:5], v[110:111] op_sel_hi:[1,0]
